# th5 plus counted waits in the first K-loop iteration of non-first FFN units: vmcnt(16) so the first two load segments do not wait for the previous epilogue's store acks
# speedup vs baseline: 1.0014x; 1.0014x over previous
.LBB0_255:
	s_ashr_i32 s17, s16, 31
	s_lshl_b64 s[8:9], s[16:17], 20
	v_readlane_b32 s18, v254, 39
	v_readlane_b32 s19, v254, 40
	s_add_u32 s18, s18, s8
	s_addc_u32 s19, s19, s9
	s_and_b64 s[8:9], s[36:37], exec
	s_cselect_b32 s8, s19, s3
	s_cselect_b32 s9, s18, s2
	s_ashr_i32 s15, s14, 31
	s_lshl_b64 s[20:21], s[14:15], 20
	s_add_u32 s20, s29, s20
	s_addc_u32 s21, s38, s21
	s_and_b64 s[26:27], s[36:37], exec
	s_cselect_b32 s15, s21, s23
	s_cselect_b32 s17, s20, s22
	s_add_u32 s2, s2, 0x80800
	s_addc_u32 s3, s3, 0
	s_add_u32 s33, s22, 0x100
	s_addc_u32 s34, s23, 0
	s_mov_b32 s35, -2
	s_add_u32 s22, s2, 0xfff80800
	s_addc_u32 s23, s3, -1
	s_add_i32 s48, 0, 0x10000
	s_cmp_eq_u32 s35, 28
	s_cselect_b32 s27, s8, s23
	s_cselect_b32 s26, s9, s22
	s_cselect_b32 s23, s15, s34
	s_cselect_b32 s22, s17, s33
	s_add_i32 s50, 0, 0x14000
	v_add_u32_e32 v176, s48, v191
	v_add_u32_e32 v188, s50, v191
	ds_read_b128 v[148:151], v176
	ds_read_b128 v[152:155], v176 offset:1024
	ds_read_b128 v[172:175], v176 offset:2048
	ds_read_b128 v[176:179], v176 offset:3072
	ds_read_b128 v[180:183], v188
	ds_read_b128 v[184:187], v188 offset:1024
	ds_read_b128 v[196:199], v188 offset:2048
	ds_read_b128 v[200:203], v188 offset:3072
	s_add_i32 m0, s39, 0xc000
	ds_read_b128 v[204:207], v194
	ds_read_b128 v[212:215], v194 offset:1024
	ds_read_b128 v[216:219], v194 offset:2048
	ds_read_b128 v[220:223], v194 offset:3072
	ds_read_b128 v[224:227], v194 offset:4096
	ds_read_b128 v[228:231], v194 offset:5120
	ds_read_b128 v[232:235], v194 offset:6144
	ds_read_b128 v[236:239], v194 offset:7168
	global_load_lds_dwordx4 v168, s[2:3]
	s_add_i32 m0, s39, 0xe000
	s_nop 0
	global_load_lds_dwordx4 v170, s[2:3]
	s_cmp_lg_u32 s46, 1
	s_cbranch_scc1 .Lpw1_relax
	s_waitcnt vmcnt(8)
	s_branch .Lpw1_join
.Lpw1_relax:
	s_waitcnt vmcnt(16)
.Lpw1_join:
	s_waitcnt lgkmcnt(0)
	s_setprio 1
	s_barrier
	v_mfma_f32_16x16x32_bf16 v[144:147], v[148:151], v[204:207], 0
	v_mfma_f32_16x16x32_bf16 v[136:139], v[172:175], v[204:207], 0
	v_mfma_f32_16x16x32_bf16 v[128:131], v[148:151], v[216:219], 0
	v_mfma_f32_16x16x32_bf16 v[120:123], v[172:175], v[216:219], 0
	v_mfma_f32_16x16x32_bf16 v[112:115], v[148:151], v[224:227], 0
	v_mfma_f32_16x16x32_bf16 v[104:107], v[172:175], v[224:227], 0
	v_mfma_f32_16x16x32_bf16 v[96:99], v[148:151], v[232:235], 0
	v_mfma_f32_16x16x32_bf16 v[88:91], v[172:175], v[232:235], 0
	v_mfma_f32_16x16x32_bf16 v[144:147], v[152:155], v[212:215], v[144:147]
	v_mfma_f32_16x16x32_bf16 v[136:139], v[176:179], v[212:215], v[136:139]
	v_mfma_f32_16x16x32_bf16 v[128:131], v[152:155], v[220:223], v[128:131]
	v_mfma_f32_16x16x32_bf16 v[120:123], v[176:179], v[220:223], v[120:123]
	v_mfma_f32_16x16x32_bf16 v[112:115], v[152:155], v[228:231], v[112:115]
	v_mfma_f32_16x16x32_bf16 v[104:107], v[176:179], v[228:231], v[104:107]
	v_mfma_f32_16x16x32_bf16 v[96:99], v[152:155], v[236:239], v[96:99]
	v_mfma_f32_16x16x32_bf16 v[88:91], v[176:179], v[236:239], v[88:91]
	v_mfma_f32_16x16x32_bf16 v[140:143], v[180:183], v[204:207], 0
	v_mfma_f32_16x16x32_bf16 v[132:135], v[196:199], v[204:207], 0
	v_mfma_f32_16x16x32_bf16 v[124:127], v[180:183], v[216:219], 0
	v_mfma_f32_16x16x32_bf16 v[116:119], v[196:199], v[216:219], 0
	v_mfma_f32_16x16x32_bf16 v[108:111], v[180:183], v[224:227], 0
	v_mfma_f32_16x16x32_bf16 v[100:103], v[196:199], v[224:227], 0
	v_mfma_f32_16x16x32_bf16 v[92:95], v[180:183], v[232:235], 0
	v_mfma_f32_16x16x32_bf16 v[84:87], v[196:199], v[232:235], 0
	v_mfma_f32_16x16x32_bf16 v[140:143], v[184:187], v[212:215], v[140:143]
	v_mfma_f32_16x16x32_bf16 v[132:135], v[200:203], v[212:215], v[132:135]
	v_mfma_f32_16x16x32_bf16 v[124:127], v[184:187], v[220:223], v[124:127]
	v_mfma_f32_16x16x32_bf16 v[116:119], v[200:203], v[220:223], v[116:119]
	v_mfma_f32_16x16x32_bf16 v[108:111], v[184:187], v[228:231], v[108:111]
	v_mfma_f32_16x16x32_bf16 v[100:103], v[200:203], v[228:231], v[100:103]
	v_mfma_f32_16x16x32_bf16 v[92:95], v[184:187], v[236:239], v[92:95]
	v_mfma_f32_16x16x32_bf16 v[84:87], v[200:203], v[236:239], v[84:87]
	s_barrier
	s_setprio 0
	s_add_i32 s48, s48, s28
	s_add_u32 s98, s22, 0x80
	s_addc_u32 s99, s23, 0
	s_add_u32 s100, s26, 0x800
	s_addc_u32 s101, s27, 0
	s_mov_b32 m0, s48
	ds_read_b128 v[204:207], v194 offset:16384
	ds_read_b128 v[212:215], v194 offset:17408
	ds_read_b128 v[216:219], v194 offset:18432
	ds_read_b128 v[220:223], v194 offset:19456
	ds_read_b128 v[224:227], v194 offset:20480
	ds_read_b128 v[228:231], v194 offset:21504
	ds_read_b128 v[232:235], v194 offset:22528
	ds_read_b128 v[236:239], v194 offset:23552
	global_load_lds_dwordx4 v2, s[22:23]
	s_add_i32 m0, s48, 0x2000
	s_add_u32 s48, s22, 0x80000
	s_addc_u32 s49, s23, 0
	s_add_i32 s50, s50, s28
	global_load_lds_dwordx4 v156, s[22:23]
	s_mov_b32 m0, s50
	s_nop 0
	global_load_lds_dwordx4 v2, s[48:49]
	s_add_i32 m0, s50, 0x2000
	s_nop 0
	global_load_lds_dwordx4 v156, s[48:49]
	s_mov_b32 m0, s39
	s_nop 0
	global_load_lds_dwordx4 v160, s[26:27]
	s_mov_b32 m0, s41
	s_nop 0
	global_load_lds_dwordx4 v158, s[26:27]
	s_cmp_lg_u32 s46, 1
	s_cbranch_scc1 .Lpw2_relax
	s_waitcnt vmcnt(8)
	s_branch .Lpw2_join

.Lpw2_join:
	s_waitcnt lgkmcnt(0)
	s_setprio 1
	s_barrier
	v_mfma_f32_16x16x32_bf16 v[80:83], v[148:151], v[204:207], 0
	v_mfma_f32_16x16x32_bf16 v[72:75], v[172:175], v[204:207], 0
	v_mfma_f32_16x16x32_bf16 v[64:67], v[148:151], v[216:219], 0
	v_mfma_f32_16x16x32_bf16 v[56:59], v[172:175], v[216:219], 0
	v_mfma_f32_16x16x32_bf16 v[48:51], v[148:151], v[224:227], 0
	v_mfma_f32_16x16x32_bf16 v[40:43], v[172:175], v[224:227], 0
	v_mfma_f32_16x16x32_bf16 v[32:35], v[148:151], v[232:235], 0
	v_mfma_f32_16x16x32_bf16 v[24:27], v[172:175], v[232:235], 0
	v_mfma_f32_16x16x32_bf16 v[80:83], v[152:155], v[212:215], v[80:83]
	v_mfma_f32_16x16x32_bf16 v[72:75], v[176:179], v[212:215], v[72:75]
	v_mfma_f32_16x16x32_bf16 v[64:67], v[152:155], v[220:223], v[64:67]
	v_mfma_f32_16x16x32_bf16 v[56:59], v[176:179], v[220:223], v[56:59]
	v_mfma_f32_16x16x32_bf16 v[48:51], v[152:155], v[228:231], v[48:51]
	v_mfma_f32_16x16x32_bf16 v[40:43], v[176:179], v[228:231], v[40:43]
	v_mfma_f32_16x16x32_bf16 v[32:35], v[152:155], v[236:239], v[32:35]
	v_mfma_f32_16x16x32_bf16 v[24:27], v[176:179], v[236:239], v[24:27]
	v_mfma_f32_16x16x32_bf16 v[76:79], v[180:183], v[204:207], 0
	v_mfma_f32_16x16x32_bf16 v[68:71], v[196:199], v[204:207], 0
	v_mfma_f32_16x16x32_bf16 v[60:63], v[180:183], v[216:219], 0
	v_mfma_f32_16x16x32_bf16 v[52:55], v[196:199], v[216:219], 0
	v_mfma_f32_16x16x32_bf16 v[44:47], v[180:183], v[224:227], 0
	v_mfma_f32_16x16x32_bf16 v[36:39], v[196:199], v[224:227], 0
	v_mfma_f32_16x16x32_bf16 v[28:31], v[180:183], v[232:235], 0
	v_mfma_f32_16x16x32_bf16 v[20:23], v[196:199], v[232:235], 0
	v_mfma_f32_16x16x32_bf16 v[76:79], v[184:187], v[212:215], v[76:79]
	v_mfma_f32_16x16x32_bf16 v[68:71], v[200:203], v[212:215], v[68:71]
	v_mfma_f32_16x16x32_bf16 v[60:63], v[184:187], v[220:223], v[60:63]
	v_mfma_f32_16x16x32_bf16 v[52:55], v[200:203], v[220:223], v[52:55]
	v_mfma_f32_16x16x32_bf16 v[44:47], v[184:187], v[228:231], v[44:47]
	v_mfma_f32_16x16x32_bf16 v[36:39], v[200:203], v[228:231], v[36:39]
	v_mfma_f32_16x16x32_bf16 v[28:31], v[184:187], v[236:239], v[28:31]
	v_mfma_f32_16x16x32_bf16 v[20:23], v[200:203], v[236:239], v[20:23]
	s_barrier
	s_setprio 0
	s_add_i32 s48, 0, 0x18000
	s_add_i32 s49, 0, 0x1c000
	v_add_u32_e32 v176, s48, v191
	v_add_u32_e32 v195, s49, v191
	ds_read_b128 v[148:151], v176
	ds_read_b128 v[152:155], v176 offset:1024
	ds_read_b128 v[172:175], v176 offset:2048
	ds_read_b128 v[176:179], v176 offset:3072
	ds_read_b128 v[180:183], v195
	ds_read_b128 v[184:187], v195 offset:1024
	ds_read_b128 v[196:199], v195 offset:2048
	ds_read_b128 v[200:203], v195 offset:3072
	s_add_u32 s26, s26, 0x80000
	s_addc_u32 s27, s27, 0
	s_mov_b32 m0, s42
	ds_read_b128 v[204:207], v194 offset:32768
	ds_read_b128 v[212:215], v194 offset:33792
	ds_read_b128 v[216:219], v194 offset:34816
	ds_read_b128 v[220:223], v194 offset:35840
	ds_read_b128 v[224:227], v194 offset:36864
	ds_read_b128 v[228:231], v194 offset:37888
	ds_read_b128 v[232:235], v194 offset:38912
	ds_read_b128 v[236:239], v194 offset:39936
	global_load_lds_dwordx4 v160, s[26:27]
	s_mov_b32 m0, s43
	s_nop 0
	global_load_lds_dwordx4 v158, s[26:27]
	s_waitcnt vmcnt(8)
	s_waitcnt lgkmcnt(0)
	s_setprio 1
	s_barrier
	v_mfma_f32_16x16x32_bf16 v[144:147], v[148:151], v[204:207], v[144:147]
	v_mfma_f32_16x16x32_bf16 v[136:139], v[172:175], v[204:207], v[136:139]
	v_mfma_f32_16x16x32_bf16 v[128:131], v[148:151], v[216:219], v[128:131]
	v_mfma_f32_16x16x32_bf16 v[120:123], v[172:175], v[216:219], v[120:123]
	v_mfma_f32_16x16x32_bf16 v[112:115], v[148:151], v[224:227], v[112:115]
	v_mfma_f32_16x16x32_bf16 v[104:107], v[172:175], v[224:227], v[104:107]
	v_mfma_f32_16x16x32_bf16 v[96:99], v[148:151], v[232:235], v[96:99]
	v_mfma_f32_16x16x32_bf16 v[88:91], v[172:175], v[232:235], v[88:91]
	v_mfma_f32_16x16x32_bf16 v[144:147], v[152:155], v[212:215], v[144:147]
	v_mfma_f32_16x16x32_bf16 v[136:139], v[176:179], v[212:215], v[136:139]
	v_mfma_f32_16x16x32_bf16 v[128:131], v[152:155], v[220:223], v[128:131]
	v_mfma_f32_16x16x32_bf16 v[120:123], v[176:179], v[220:223], v[120:123]
	v_mfma_f32_16x16x32_bf16 v[112:115], v[152:155], v[228:231], v[112:115]
	v_mfma_f32_16x16x32_bf16 v[104:107], v[176:179], v[228:231], v[104:107]
	v_mfma_f32_16x16x32_bf16 v[96:99], v[152:155], v[236:239], v[96:99]
	v_mfma_f32_16x16x32_bf16 v[88:91], v[176:179], v[236:239], v[88:91]
	v_mfma_f32_16x16x32_bf16 v[140:143], v[180:183], v[204:207], v[140:143]
	v_mfma_f32_16x16x32_bf16 v[132:135], v[196:199], v[204:207], v[132:135]
	v_mfma_f32_16x16x32_bf16 v[124:127], v[180:183], v[216:219], v[124:127]
	v_mfma_f32_16x16x32_bf16 v[116:119], v[196:199], v[216:219], v[116:119]
	v_mfma_f32_16x16x32_bf16 v[108:111], v[180:183], v[224:227], v[108:111]
	v_mfma_f32_16x16x32_bf16 v[100:103], v[196:199], v[224:227], v[100:103]
	v_mfma_f32_16x16x32_bf16 v[92:95], v[180:183], v[232:235], v[92:95]
	v_mfma_f32_16x16x32_bf16 v[84:87], v[196:199], v[232:235], v[84:87]
	v_mfma_f32_16x16x32_bf16 v[140:143], v[184:187], v[212:215], v[140:143]
	v_mfma_f32_16x16x32_bf16 v[132:135], v[200:203], v[212:215], v[132:135]
	v_mfma_f32_16x16x32_bf16 v[124:127], v[184:187], v[220:223], v[124:127]
	v_mfma_f32_16x16x32_bf16 v[116:119], v[200:203], v[220:223], v[116:119]
	v_mfma_f32_16x16x32_bf16 v[108:111], v[184:187], v[228:231], v[108:111]
	v_mfma_f32_16x16x32_bf16 v[100:103], v[200:203], v[228:231], v[100:103]
	v_mfma_f32_16x16x32_bf16 v[92:95], v[184:187], v[236:239], v[92:95]
	v_mfma_f32_16x16x32_bf16 v[84:87], v[200:203], v[236:239], v[84:87]
	s_barrier
	s_setprio 0
	s_add_i32 s26, s48, s28
	s_mov_b32 m0, s26
	ds_read_b128 v[204:207], v194 offset:49152
	ds_read_b128 v[212:215], v194 offset:50176
	ds_read_b128 v[216:219], v194 offset:51200
	ds_read_b128 v[220:223], v194 offset:52224
	ds_read_b128 v[224:227], v194 offset:53248
	ds_read_b128 v[228:231], v194 offset:54272
	ds_read_b128 v[232:235], v194 offset:55296
	ds_read_b128 v[236:239], v194 offset:56320
	global_load_lds_dwordx4 v2, s[98:99]
	s_add_i32 m0, s26, 0x2000
	s_add_u32 s22, s22, 0x80080
	s_addc_u32 s23, s23, 0
	s_add_i32 s26, s49, s28
	global_load_lds_dwordx4 v156, s[98:99]
	s_mov_b32 m0, s26
	s_nop 0
	global_load_lds_dwordx4 v2, s[22:23]
	s_add_i32 m0, s26, 0x2000
	s_nop 0
	global_load_lds_dwordx4 v156, s[22:23]
	s_mov_b32 m0, s44
	s_nop 0
	global_load_lds_dwordx4 v160, s[100:101]
	s_mov_b32 m0, s45
	s_nop 0
	global_load_lds_dwordx4 v158, s[100:101]
	s_waitcnt vmcnt(8)
	s_waitcnt lgkmcnt(0)
	s_setprio 1
	s_barrier
	v_mfma_f32_16x16x32_bf16 v[80:83], v[148:151], v[204:207], v[80:83]
	v_mfma_f32_16x16x32_bf16 v[72:75], v[172:175], v[204:207], v[72:75]
	v_mfma_f32_16x16x32_bf16 v[64:67], v[148:151], v[216:219], v[64:67]
	v_mfma_f32_16x16x32_bf16 v[56:59], v[172:175], v[216:219], v[56:59]
	v_mfma_f32_16x16x32_bf16 v[48:51], v[148:151], v[224:227], v[48:51]
	v_mfma_f32_16x16x32_bf16 v[40:43], v[172:175], v[224:227], v[40:43]
	v_mfma_f32_16x16x32_bf16 v[32:35], v[148:151], v[232:235], v[32:35]
	v_mfma_f32_16x16x32_bf16 v[24:27], v[172:175], v[232:235], v[24:27]
	v_mfma_f32_16x16x32_bf16 v[80:83], v[152:155], v[212:215], v[80:83]
	v_mfma_f32_16x16x32_bf16 v[72:75], v[176:179], v[212:215], v[72:75]
	v_mfma_f32_16x16x32_bf16 v[64:67], v[152:155], v[220:223], v[64:67]
	v_mfma_f32_16x16x32_bf16 v[56:59], v[176:179], v[220:223], v[56:59]
	v_mfma_f32_16x16x32_bf16 v[48:51], v[152:155], v[228:231], v[48:51]
	v_mfma_f32_16x16x32_bf16 v[40:43], v[176:179], v[228:231], v[40:43]
	v_mfma_f32_16x16x32_bf16 v[32:35], v[152:155], v[236:239], v[32:35]
	v_mfma_f32_16x16x32_bf16 v[24:27], v[176:179], v[236:239], v[24:27]
	v_mfma_f32_16x16x32_bf16 v[76:79], v[180:183], v[204:207], v[76:79]
	v_mfma_f32_16x16x32_bf16 v[68:71], v[196:199], v[204:207], v[68:71]
	v_mfma_f32_16x16x32_bf16 v[60:63], v[180:183], v[216:219], v[60:63]
	v_mfma_f32_16x16x32_bf16 v[52:55], v[196:199], v[216:219], v[52:55]
	v_mfma_f32_16x16x32_bf16 v[44:47], v[180:183], v[224:227], v[44:47]
	v_mfma_f32_16x16x32_bf16 v[36:39], v[196:199], v[224:227], v[36:39]
	v_mfma_f32_16x16x32_bf16 v[28:31], v[180:183], v[232:235], v[28:31]
	v_mfma_f32_16x16x32_bf16 v[20:23], v[196:199], v[232:235], v[20:23]
	v_mfma_f32_16x16x32_bf16 v[76:79], v[184:187], v[212:215], v[76:79]
	v_mfma_f32_16x16x32_bf16 v[68:71], v[200:203], v[212:215], v[68:71]
	v_mfma_f32_16x16x32_bf16 v[60:63], v[184:187], v[220:223], v[60:63]
	v_mfma_f32_16x16x32_bf16 v[52:55], v[200:203], v[220:223], v[52:55]
	v_mfma_f32_16x16x32_bf16 v[44:47], v[184:187], v[228:231], v[44:47]
	v_mfma_f32_16x16x32_bf16 v[36:39], v[200:203], v[228:231], v[36:39]
	v_mfma_f32_16x16x32_bf16 v[28:31], v[184:187], v[236:239], v[28:31]
	v_mfma_f32_16x16x32_bf16 v[20:23], v[200:203], v[236:239], v[20:23]
	s_barrier
	s_setprio 0
	s_add_i32 s35, s35, 2
	s_add_u32 s2, s2, 0x1000
	s_addc_u32 s3, s3, 0
	s_add_u32 s33, s33, 0x100
	s_addc_u32 s34, s34, 0
	s_cmp_gt_u32 s35, 29
	s_cbranch_scc0 .LBB0_256
	s_branch .Lpeel_done_256
